# SSD: acc=C*state and S=B*C^T MFMA chains read all LDS operands up front (8 buffers, counted lgkmcnt) instead of read-wait-MFMA per step
# baseline (speedup 1.0000x reference)
; DI int opaque_i(int v) { asm volatile("" : "+v"(v)); return v; }
; #define MFMA32(a, b, c) __builtin_amdgcn_mfma_f32_32x32x16_bf16((a), (b), (c), 0, 0, 0)
; DI void ssd_pair_item(const Params& P, unsigned char* smem, int b, int hp) {
;     ...
;         {
;             const int l32 = opaque_i(l32o), hh = opaque_i(hho);
;             const int l = 32 * lt + l32;
;             const unsigned char* cfp = smem + S2_CS + l * RS + 16 * hh;
;     ...
;             f32x16 acc;
; #pragma unroll
;             for (int i = 0; i < 16; ++i) acc[i] = 0.f;
; #pragma unroll
;             for (int ks = 0; ks < 8; ++ks) { const bf16x8 a = *(const bf16x8*)(hb + S2_ST + (32 * ph + l32) * RS + (16 * ks + 8 * hh) * 2); acc = MFMA32(a, CF2(ks), acc); }
;             const float cl = cum[l];
;             { const float e = __expf(cl);
; #pragma unroll
;               for (int i = 0; i < 16; ++i) acc[i] *= e; }
;             for (int st = 0; st <= lt; ++st) {
;                 f32x16 S;
; #pragma unroll
;                 for (int i = 0; i < 16; ++i) S[i] = 0.f;
; #pragma unroll
;                 for (int ks = 0; ks < 8; ++ks) { const bf16x8 a = *(const bf16x8*)(smem + S2_BS + (32 * st + l32) * RS + (16 * ks + 8 * hh) * 2); S = MFMA32(a, CF2(ks), S); }
.LBB0_313:
.LBB0_314:
	v_mov_b32_e32 v202, v195
	v_lshlrev_b32_e32 v201, 5, v198
	v_add_u32_e32 v175, 1, v198
	v_add_u32_e32 v174, v202, v201
	v_mul_lo_u32 v32, v174, s84
	v_lshlrev_b32_e32 v172, 4, v200
	v_add_u32_e32 v203, v202, v197
	v_add3_u32 v52, 0, v32, v172
	v_mul_lo_u32 v32, v203, s84
	v_add3_u32 v53, v192, v32, v172
	ds_read_b128 v[120:123], v52 offset:17408
	ds_read_b128 v[32:35], v53 offset:62464
	ds_read_b128 v[124:127], v52 offset:17440
	ds_read_b128 v[48:51], v53 offset:62496
	ds_read_b128 v[128:131], v52 offset:17472
	ds_read_b128 v[224:227], v53 offset:62528
	ds_read_b128 v[132:135], v52 offset:17504
	ds_read_b128 v[228:231], v53 offset:62560
	ds_read_b128 v[136:139], v52 offset:17536
	ds_read_b128 v[232:235], v53 offset:62592
	ds_read_b128 v[140:143], v52 offset:17568
	ds_read_b128 v[240:243], v53 offset:62624
	ds_read_b128 v[144:147], v52 offset:17600
	ds_read_b128 v[244:247], v53 offset:62656
	ds_read_b128 v[148:151], v52 offset:17632
	v_lshlrev_b32_e32 v204, 2, v200
	v_mad_u64_u32 v[176:177], s[0:1], v202, s84, v[172:173]
	v_mov_b32_e32 v153, v174
	v_add_u32_e32 v206, v190, v172
	s_mov_b64 s[2:3], 0
	v_mov_b32_e32 v177, v204
	s_waitcnt lgkmcnt(13)
	v_mfma_f32_32x32x16_bf16 v[32:47], v[32:35], v[120:123], 0
	ds_read_b128 v[248:251], v53 offset:62688
	s_waitcnt lgkmcnt(12)
	v_mfma_f32_32x32x16_bf16 v[32:47], v[48:51], v[124:127], v[32:47]
	s_waitcnt lgkmcnt(10)
	v_mfma_f32_32x32x16_bf16 v[32:47], v[224:227], v[128:131], v[32:47]
	s_waitcnt lgkmcnt(8)
	v_mfma_f32_32x32x16_bf16 v[32:47], v[228:231], v[132:135], v[32:47]
	s_waitcnt lgkmcnt(6)
	v_mfma_f32_32x32x16_bf16 v[32:47], v[232:235], v[136:139], v[32:47]
	s_waitcnt lgkmcnt(4)
	v_mfma_f32_32x32x16_bf16 v[32:47], v[240:243], v[140:143], v[32:47]
	s_waitcnt lgkmcnt(2)
	v_mfma_f32_32x32x16_bf16 v[32:47], v[244:247], v[144:147], v[32:47]
	s_waitcnt lgkmcnt(0)
	v_mfma_f32_32x32x16_bf16 v[32:47], v[248:251], v[148:151], v[32:47]
	v_lshl_add_u32 v48, v174, 2, v193
	ds_read_b32 v64, v48 offset:45056
	v_mul_lo_u32 v50, v202, s92
	s_waitcnt lgkmcnt(0)
	v_mul_f32_e32 v48, 0x3fb8aa3b, v64
	v_exp_f32_e32 v48, v48
	s_nop 5
	v_pk_mul_f32 v[46:47], v[46:47], v[48:49] op_sel_hi:[1,0]
	v_pk_mul_f32 v[44:45], v[44:45], v[48:49] op_sel_hi:[1,0]
	v_pk_mul_f32 v[42:43], v[42:43], v[48:49] op_sel_hi:[1,0]
	v_pk_mul_f32 v[40:41], v[40:41], v[48:49] op_sel_hi:[1,0]
	v_pk_mul_f32 v[38:39], v[38:39], v[48:49] op_sel_hi:[1,0]
	v_pk_mul_f32 v[36:37], v[36:37], v[48:49] op_sel_hi:[1,0]
	v_pk_mul_f32 v[34:35], v[34:35], v[48:49] op_sel_hi:[1,0]
	v_pk_mul_f32 v[32:33], v[32:33], v[48:49] op_sel_hi:[1,0]
	v_lshlrev_b32_e32 v48, 3, v200
	v_mad_u32_u24 v49, v199, s93, v194
	v_add3_u32 v205, v49, v50, v48
.LBB0_315:
	v_add_u32_e32 v207, 0, v176
	ds_read_b128 v[48:51], v207
	ds_read_b128 v[208:211], v207 offset:32
	ds_read_b128 v[224:227], v207 offset:64
	ds_read_b128 v[228:231], v207 offset:96
	ds_read_b128 v[232:235], v207 offset:128
	ds_read_b128 v[240:243], v207 offset:160
	ds_read_b128 v[244:247], v207 offset:192
	ds_read_b128 v[248:251], v207 offset:224
	v_add_u32_e32 v212, 0, v206
	v_cmp_le_i32_e32 vcc, v177, v174
	v_add_u32_e32 v175, -1, v175
	v_add_u32_e32 v206, 0x80, v206
	v_add_u32_e32 v176, 0x2200, v176
	s_waitcnt lgkmcnt(7)
	v_mfma_f32_32x32x16_bf16 v[48:63], v[48:51], v[120:123], 0
	s_waitcnt lgkmcnt(6)
	v_mfma_f32_32x32x16_bf16 v[48:63], v[208:211], v[124:127], v[48:63]
	s_waitcnt lgkmcnt(5)
	v_mfma_f32_32x32x16_bf16 v[48:63], v[224:227], v[128:131], v[48:63]
	s_waitcnt lgkmcnt(4)
	v_mfma_f32_32x32x16_bf16 v[48:63], v[228:231], v[132:135], v[48:63]
	s_waitcnt lgkmcnt(3)
	v_mfma_f32_32x32x16_bf16 v[48:63], v[232:235], v[136:139], v[48:63]
	s_waitcnt lgkmcnt(2)
	v_mfma_f32_32x32x16_bf16 v[48:63], v[240:243], v[140:143], v[48:63]
	s_waitcnt lgkmcnt(1)
	v_mfma_f32_32x32x16_bf16 v[48:63], v[244:247], v[144:147], v[48:63]
	s_waitcnt lgkmcnt(0)
	v_mfma_f32_32x32x16_bf16 v[48:63], v[248:251], v[148:151], v[48:63]
	v_add_u32_e32 v207, 0x13800, v212
	ds_read_b128 v[208:211], v207
	v_add_u32_e32 v207, 0x13a00, v212
	ds_read_b128 v[216:219], v207
	s_waitcnt lgkmcnt(1)
	v_sub_f32_e32 v207, v64, v208
	v_min_f32_e32 v207, 0, v207
	v_mul_f32_e32 v207, 0x3fb8aa3b, v207
	v_exp_f32_e32 v207, v207
	s_waitcnt lgkmcnt(0)
	v_mul_f32_e32 v207, v216, v207
	s_nop 1
	v_mul_f32_e32 v48, v48, v207
	v_cndmask_b32_e32 v208, 0, v48, vcc
	v_sub_f32_e32 v48, v64, v209
	v_min_f32_e32 v48, 0, v48
	v_mul_f32_e32 v48, 0x3fb8aa3b, v48
	v_exp_f32_e32 v48, v48
	v_cmp_lt_i32_e32 vcc, v177, v174
	v_add_u32_e32 v207, 8, v177
	v_mul_f32_e32 v48, v217, v48
	v_mul_f32_e32 v48, v49, v48
	v_cndmask_b32_e32 v209, 0, v48, vcc
	v_sub_f32_e32 v48, v64, v210
	v_sub_f32_e32 v49, v64, v211
	v_min_f32_e32 v48, 0, v48
	v_min_f32_e32 v49, 0, v49
	v_mul_f32_e32 v48, 0x3fb8aa3b, v48
	v_mul_f32_e32 v49, 0x3fb8aa3b, v49
	v_exp_f32_e32 v48, v48
	v_exp_f32_e32 v49, v49
	v_cmp_le_i32_e32 vcc, v207, v174
	v_or_b32_e32 v211, 2, v177
	v_or_b32_e32 v210, 3, v177
	v_pk_mul_f32 v[48:49], v[218:219], v[48:49]
	v_cvt_pk_bf16_f32 v208, v208, v209
	v_pk_mul_f32 v[48:49], v[50:51], v[48:49]
	v_add_u32_e32 v50, 0x13820, v212
	ds_read_b128 v[216:219], v50
	v_add_u32_e32 v50, 0x13a20, v212
	ds_read_b128 v[220:223], v50
	v_cvt_pk_bf16_f32 v48, v48, v49
	s_waitcnt lgkmcnt(1)
; #define MFMA32(a, b, c) __builtin_amdgcn_mfma_f32_32x32x16_bf16((a), (b), (c), 0, 0, 0)
; DI bf16x8 cat44(s16x4 a, s16x4 b) { return __builtin_shufflevector(a, b, 0, 1, 2, 3, 4, 5, 6, 7); }
; DI void ssd_pair_item(const Params& P, unsigned char* smem, int b, int hp) {
;     ...
; #pragma unroll
;                 for (int ig = 0; ig < 4; ++ig) { const int s0 = 32 * st + 8 * ig + 4 * hh; const f32x4 cs = *(const f32x4*)(cum + s0), dv = *(const f32x4*)(dtv + s0);
; #pragma unroll
;                     for (int j = 0; j < 4; ++j) { const float dec = __expf(fminf(cl - cs[j], 0.f)) * dv[j]; S[4 * ig + j] = (s0 + j <= l) ? S[4 * ig + j] * dec : 0.f; } }
; #pragma unroll
;                 for (int s2 = 0; s2 < 2; ++s2) {
;                     const bf16x8 mf = pack8(S, s2);
;                     const unsigned char* xp = hb + S2_XT + (32 * ph + l32) * RS2 + (32 * st + 16 * s2 + 4 * hh) * 2;
;                     const bf16x8 a = cat44(*(const s16x4*)xp, *(const s16x4*)(xp + 16));
;                     acc = MFMA32(a, mf, acc);
;                 }
;             }
	v_sub_f32_e32 v50, v64, v216
	v_min_f32_e32 v50, 0, v50
	v_mul_f32_e32 v50, 0x3fb8aa3b, v50
	v_exp_f32_e32 v50, v50
	v_sub_f32_e32 v51, v64, v219
	v_min_f32_e32 v51, 0, v51
	v_mul_f32_e32 v51, 0x3fb8aa3b, v51
	s_waitcnt lgkmcnt(0)
	v_mul_f32_e32 v50, v220, v50
	v_mul_f32_e32 v50, v52, v50
	v_cndmask_b32_e32 v213, 0, v50, vcc
	v_sub_f32_e32 v50, v64, v217
	v_min_f32_e32 v50, 0, v50
	v_mul_f32_e32 v50, 0x3fb8aa3b, v50
	v_exp_f32_e32 v50, v50
	v_cmp_lt_i32_e32 vcc, v207, v174
	v_exp_f32_e32 v51, v51
	v_add_u32_e32 v52, 0x13840, v212
	v_mul_f32_e32 v50, v221, v50
	v_mul_f32_e32 v50, v53, v50
	v_cndmask_b32_e32 v214, 0, v50, vcc
	v_sub_f32_e32 v50, v64, v218
	v_min_f32_e32 v50, 0, v50
	v_mul_f32_e32 v50, 0x3fb8aa3b, v50
	v_exp_f32_e32 v50, v50
	v_add_u32_e32 v216, 0x13a40, v212
	ds_read_b128 v[216:219], v216
	v_or_b32_e32 v220, 3, v207
	v_pk_mul_f32 v[50:51], v[222:223], v[50:51]
	v_or_b32_e32 v221, 2, v207
	v_pk_mul_f32 v[50:51], v[54:55], v[50:51]
	ds_read_b128 v[52:55], v52
	v_add_u32_e32 v207, 16, v177
	v_cmp_le_i32_e32 vcc, v207, v174
	v_add_u32_e32 v223, 24, v177
	v_add_u32_e32 v177, 32, v177
	s_waitcnt lgkmcnt(0)
	v_sub_f32_e32 v52, v64, v52
	v_min_f32_e32 v52, 0, v52
	v_sub_f32_e32 v53, v64, v53
	v_mul_f32_e32 v52, 0x3fb8aa3b, v52
	v_min_f32_e32 v53, 0, v53
	v_exp_f32_e32 v52, v52
	v_mul_f32_e32 v53, 0x3fb8aa3b, v53
	v_exp_f32_e32 v53, v53
	v_mul_f32_e32 v52, v216, v52
	v_mul_f32_e32 v52, v56, v52
	v_mul_f32_e32 v53, v217, v53
	v_cndmask_b32_e32 v52, 0, v52, vcc
	v_cmp_lt_i32_e32 vcc, v207, v174
	v_mul_f32_e32 v53, v57, v53
	v_add_u32_e32 v56, 0x13860, v212
	v_cndmask_b32_e32 v222, 0, v53, vcc
	v_sub_f32_e32 v53, v64, v54
	v_min_f32_e32 v53, 0, v53
	v_mul_f32_e32 v53, 0x3fb8aa3b, v53
	v_exp_f32_e32 v54, v53
	v_sub_f32_e32 v53, v64, v55
	v_min_f32_e32 v53, 0, v53
	v_mul_f32_e32 v53, 0x3fb8aa3b, v53
	v_exp_f32_e32 v55, v53
	v_add_u32_e32 v212, 0x13a60, v212
	v_cmp_le_i32_e32 vcc, v223, v174
	v_or_b32_e32 v53, 3, v207
	v_pk_mul_f32 v[54:55], v[218:219], v[54:55]
	ds_read_b128 v[216:219], v212
	v_pk_mul_f32 v[54:55], v[58:59], v[54:55]
	ds_read_b128 v[56:59], v56
	v_or_b32_e32 v207, 2, v207
	v_cvt_pk_bf16_f32 v54, v54, v55
	v_cvt_pk_bf16_f32 v52, v52, v222
	s_waitcnt lgkmcnt(0)
	v_sub_f32_e32 v56, v64, v56
	v_min_f32_e32 v56, 0, v56
	v_mul_f32_e32 v56, 0x3fb8aa3b, v56
	v_exp_f32_e32 v56, v56
	s_nop 0
	v_mul_f32_e32 v56, v216, v56
	v_mul_f32_e32 v56, v60, v56
	v_cndmask_b32_e32 v60, 0, v56, vcc
	v_sub_f32_e32 v56, v64, v57
	v_min_f32_e32 v56, 0, v56
	v_mul_f32_e32 v56, 0x3fb8aa3b, v56
	v_exp_f32_e32 v56, v56
	v_cmp_lt_i32_e32 vcc, v223, v174
	v_sub_f32_e32 v57, v64, v59
	v_min_f32_e32 v57, 0, v57
	v_mul_f32_e32 v56, v217, v56
	v_mul_f32_e32 v56, v61, v56
	v_cndmask_b32_e32 v61, 0, v56, vcc
	v_sub_f32_e32 v56, v64, v58
	v_min_f32_e32 v56, 0, v56
	v_mul_f32_e32 v56, 0x3fb8aa3b, v56
	v_mul_f32_e32 v57, 0x3fb8aa3b, v57
	v_exp_f32_e32 v56, v56
	v_exp_f32_e32 v57, v57
	v_cmp_le_i32_e32 vcc, v211, v174
	v_or_b32_e32 v59, 2, v223
	v_or_b32_e32 v58, 3, v223
	v_cndmask_b32_e32 v49, 0, v48, vcc
	v_lshrrev_b32_e32 v48, 16, v48
	v_cmp_le_i32_e32 vcc, v210, v153
	v_pk_mul_f32 v[56:57], v[218:219], v[56:57]
	v_cvt_pk_bf16_f32 v210, v213, v214
	v_cndmask_b32_e32 v48, 0, v48, vcc
	v_perm_b32 v209, v48, v49, s94
	v_cvt_pk_bf16_f32 v48, v50, v51
	v_cmp_le_i32_e32 vcc, v221, v174
	v_pk_mul_f32 v[56:57], v[62:63], v[56:57]
	v_add_u32_e32 v62, 0, v205
	v_cndmask_b32_e32 v49, 0, v48, vcc
	v_lshrrev_b32_e32 v48, 16, v48
	v_cmp_le_i32_e32 vcc, v220, v153
	v_add_u32_e32 v205, 64, v205
	s_nop 0
	v_cndmask_b32_e32 v48, 0, v48, vcc
	v_perm_b32 v211, v48, v49, s94
	ds_read2_b64 v[216:219], v62 offset1:2
	ds_read2_b64 v[48:51], v62 offset0:4 offset1:6
	s_waitcnt lgkmcnt(1)
	v_mfma_f32_32x32x16_bf16 v[32:47], v[216:219], v[208:211], v[32:47]
	v_cmp_le_i32_e32 vcc, v207, v174
	s_nop 1
	v_cndmask_b32_e32 v55, 0, v54, vcc
	v_lshrrev_b32_e32 v54, 16, v54
	v_cmp_le_i32_e32 vcc, v53, v153
	s_nop 1
	v_cndmask_b32_e32 v53, 0, v54, vcc
	v_perm_b32 v53, v53, v55, s94
	v_cvt_pk_bf16_f32 v55, v56, v57
	v_cmp_le_i32_e32 vcc, v59, v174
	v_cvt_pk_bf16_f32 v54, v60, v61
	s_nop 0
	v_cndmask_b32_e32 v56, 0, v55, vcc
	v_lshrrev_b32_e32 v55, 16, v55
	v_cmp_le_i32_e32 vcc, v58, v153
	s_nop 1
	v_cndmask_b32_e32 v55, 0, v55, vcc
	v_perm_b32 v55, v55, v56, s94
	v_cmp_eq_u32_e32 vcc, 0, v175
	s_or_b64 s[2:3], vcc, s[2:3]
	s_waitcnt lgkmcnt(0)
	v_mfma_f32_32x32x16_bf16 v[32:47], v[48:51], v[52:55], v[32:47]
	s_andn2_b64 exec, exec, s[2:3]
	s_cbranch_execnz .LBB0_315
	s_or_b64 exec, exec, s[2:3]
	v_add_u32_e32 v52, v204, v197
	v_mul_lo_u32 v50, v52, s92
	v_lshl_add_u32 v50, v174, 1, v50
	s_cmp_eq_u32 s33, 31
	s_cbranch_scc1 .Lssd_wA_0
	s_waitcnt vmcnt(13)
	s_branch .Lssd_wB_0
